# helper priority raised only during the PREP passes (derive/M tail at normal priority)
# speedup vs baseline: 1.0329x; 1.0329x over previous
.Lmy_f_nol34:
	s_waitcnt lgkmcnt(0)
	s_setprio 0
	s_bfe_u32 s96, s62, 0x20006
	s_lshl_b32 s100, s96, 11
	v_lshl_add_u32 v72, v224, 2, s100
	s_and_b32 s97, s96, 1
	s_mul_i32 s97, s97, 0x2700
	s_mov_b32 s101, 0x1c000
	s_mov_b32 s100, 0x6100
	s_bitcmp0_b32 s65, 0
	s_cselect_b32 s101, 0xe000, s101
	s_cselect_b32 s100, 0x4e00, s100
	s_cmp_gt_u32 s96, 1
	s_cselect_b32 s100, s100, 0
	s_add_i32 s97, s97, s101
	s_add_i32 s97, s97, s100
	ds_read_b32 v80, v72
	ds_read_b32 v81, v72 offset:256
	ds_read_b32 v82, v72 offset:512
	ds_read_b32 v83, v72 offset:768
	ds_read_b32 v84, v72 offset:1024
	ds_read_b32 v85, v72 offset:1280
	ds_read_b32 v86, v72 offset:1536
	ds_read_b32 v87, v72 offset:1792
	ds_read_b32 v88, v72 offset:8192
	ds_read_b32 v89, v72 offset:8448
	ds_read_b32 v90, v72 offset:8704
	ds_read_b32 v91, v72 offset:8960
	ds_read_b32 v92, v72 offset:9216
	ds_read_b32 v93, v72 offset:9472
	ds_read_b32 v94, v72 offset:9728
	ds_read_b32 v95, v72 offset:9984
	ds_read_b32 v96, v72 offset:32768
	ds_read_b32 v97, v72 offset:33024
	ds_read_b32 v98, v72 offset:33280
	ds_read_b32 v99, v72 offset:33536
	ds_read_b32 v100, v72 offset:33792
	ds_read_b32 v101, v72 offset:34048
	ds_read_b32 v102, v72 offset:34304
	ds_read_b32 v103, v72 offset:34560
	v_and_b32_e32 v74, 3, v224
	v_bfe_u32 v75, v224, 2, 2
	v_lshrrev_b32_e32 v76, 4, v224
	v_lshlrev_b32_e32 v74, 2, v74
	v_lshl_add_u32 v74, v75, 8, v74
	v_lshl_add_u32 v74, v76, 10, v74
	s_add_i32 s100, s97, 0x0
	v_add_u32_e32 v74, s100, v74
	v_xor_b32_e32 v76, 0, v75
	v_xor_b32_e32 v77, 1, v75
	v_xor_b32_e32 v78, 2, v75
	v_xor_b32_e32 v79, 3, v75
	v_lshl_add_u32 v76, v76, 4, v74
	v_lshl_add_u32 v77, v77, 4, v74
	v_lshl_add_u32 v78, v78, 4, v74
	v_lshl_add_u32 v79, v79, 4, v74
	s_waitcnt lgkmcnt(7)
	v_mov_b32_e32 v104, v80
	v_mul_f32_e32 v105, v104, v81
	v_mul_f32_e32 v106, v105, v82
	v_mul_f32_e32 v107, v106, v83
	v_mul_f32_e32 v108, v107, v84
	v_mul_f32_e32 v109, v108, v85
	v_mul_f32_e32 v110, v109, v86
	v_mul_f32_e32 v111, v110, v87
	v_mov_b32_e32 v112, v88
	v_mul_f32_e32 v113, v104, v89
	v_mul_f32_e32 v114, v105, v90
	v_mul_f32_e32 v115, v106, v91
	v_mul_f32_e32 v116, v107, v92
	v_mul_f32_e32 v117, v108, v93
	v_mul_f32_e32 v118, v109, v94
	v_mul_f32_e32 v119, v110, v95
	v_mul_f32_e32 v120, v104, v96
	s_waitcnt lgkmcnt(0)
	v_mul_f32_e32 v121, v105, v97
	v_mul_f32_e32 v122, v106, v98
	v_mul_f32_e32 v123, v107, v99
	v_mul_f32_e32 v124, v108, v100
	v_mul_f32_e32 v125, v109, v101
	v_mul_f32_e32 v126, v110, v102
	v_mul_f32_e32 v127, v111, v103
	ds_write_b32 v76, v112
	ds_write_b32 v77, v113
	ds_write_b32 v78, v114
	ds_write_b32 v79, v115
	ds_write_b32 v76, v116 offset:64
	ds_write_b32 v77, v117 offset:64
	ds_write_b32 v78, v118 offset:64
	ds_write_b32 v79, v119 offset:64
	ds_write_b32 v76, v120 offset:128
	ds_write_b32 v77, v121 offset:128
	ds_write_b32 v78, v122 offset:128
	ds_write_b32 v79, v123 offset:128
	ds_write_b32 v76, v124 offset:192
	ds_write_b32 v77, v125 offset:192
	ds_write_b32 v78, v126 offset:192
	ds_write_b32 v79, v127 offset:192

.Lmy_ck_drE_h:
	s_waitcnt lgkmcnt(0)
	s_bfe_u32 s96, s62, 0x20006
	s_and_b32 s97, s96, 1
	s_mul_i32 s97, s97, 0x2700
	s_mov_b32 s101, 0x1c000
	s_mov_b32 s100, 0x6100
	s_bitcmp0_b32 s65, 0
	s_cselect_b32 s101, 0xe000, s101
	s_cselect_b32 s100, 0x4e00, s100
	s_cmp_gt_u32 s96, 1
	s_cselect_b32 s100, s100, 0
	s_add_i32 s97, s97, s101
	s_add_i32 s97, s97, s100
	s_mov_b32 s96, s97
	v_and_b32_e32 v72, 3, v233
	v_lshrrev_b32_e32 v73, 2, v233
	v_lshlrev_b32_e32 v72, 2, v72
	v_lshl_add_u32 v72, v73, 8, v72
	v_lshl_add_u32 v72, v234, 6, v72
	s_add_i32 s97, s96, 0x1000
	v_add_u32_e32 v78, s97, v72
	v_xor_b32_e32 v79, v224, v234
	v_lshl_add_u32 v79, v79, 4, s96
	ds_read_b128 v[96:99], v79
	ds_read_b128 v[100:103], v79 offset:1024
	ds_read_b128 v[104:107], v79 offset:2048
	ds_read_b128 v[108:111], v79 offset:3072
	ds_read_b32 v80, v78
	ds_read_b32 v81, v78 offset:16
	ds_read_b32 v82, v78 offset:32
	ds_read_b32 v83, v78 offset:48
	ds_read_b32 v84, v78 offset:1024
	ds_read_b32 v85, v78 offset:1040
	ds_read_b32 v86, v78 offset:1056
	ds_read_b32 v87, v78 offset:1072
	ds_read_b32 v88, v78 offset:2048
	ds_read_b32 v89, v78 offset:2064
	ds_read_b32 v90, v78 offset:2080
	ds_read_b32 v91, v78 offset:2096
	ds_read_b32 v92, v78 offset:3072
	ds_read_b32 v93, v78 offset:3088
	ds_read_b32 v94, v78 offset:3104
	ds_read_b32 v95, v78 offset:3120
	v_lshl_add_u32 v74, v224, 2, s96
	ds_write_b32 v74, v235 offset:9728
	v_add_u32_e32 v75, -1, v233
	v_mov_b32_e32 v76, -1
	v_cndmask_b32_e64 v75, v76, v75, s[98:99]
	v_cmp_lt_u32_e64 s[100:101], 7, v233
	v_add_u32_e32 v76, -8, v233
	v_and_b32_e32 v77, 1, v234
	v_cndmask_b32_e64 v75, v75, v76, s[100:101]
	v_lshlrev_b32_e32 v77, 2, v77
	v_sub_u32_e32 v76, v75, v77
	v_lshlrev_b32_e32 v77, 2, v234
	v_sub_u32_e32 v77, v233, v77
	v_add_u32_e32 v77, -1, v77
	s_waitcnt lgkmcnt(10)
	v_mfma_f32_16x16x4_f32 v[244:247], v80, v96, 0
	v_mfma_f32_16x16x4_f32 v[240:243], v81, v97, 0
	v_mfma_f32_16x16x4_f32 v[244:247], v82, v98, v[244:247]
	v_mfma_f32_16x16x4_f32 v[240:243], v83, v99, v[240:243]
	v_mfma_f32_16x16x4_f32 v[244:247], v84, v100, v[244:247]
	v_mfma_f32_16x16x4_f32 v[240:243], v85, v101, v[240:243]
	v_mfma_f32_16x16x4_f32 v[244:247], v86, v102, v[244:247]
	s_waitcnt lgkmcnt(2)
	v_mfma_f32_16x16x4_f32 v[240:243], v87, v103, v[240:243]
	v_mfma_f32_16x16x4_f32 v[244:247], v88, v104, v[244:247]
	v_mfma_f32_16x16x4_f32 v[240:243], v89, v105, v[240:243]
	v_mfma_f32_16x16x4_f32 v[244:247], v90, v106, v[244:247]
	v_mfma_f32_16x16x4_f32 v[240:243], v91, v107, v[240:243]
	v_mfma_f32_16x16x4_f32 v[244:247], v92, v108, v[244:247]
	v_mfma_f32_16x16x4_f32 v[240:243], v93, v109, v[240:243]
	v_mfma_f32_16x16x4_f32 v[244:247], v94, v110, v[244:247]
	s_waitcnt lgkmcnt(1)
	v_mfma_f32_16x16x4_f32 v[240:243], v95, v111, v[240:243]
	s_nop 9
	v_add_f32_e32 v244, v244, v240
	v_add_f32_e32 v245, v245, v241
	v_add_f32_e32 v246, v246, v242
	v_add_f32_e32 v247, v247, v243
	v_cmp_le_i32_e64 s[96:97], 0, v76
	v_cmp_le_i32_e64 s[100:101], 1, v76
	s_nop 0
	v_cndmask_b32_e64 v128, 0, v244, s[96:97]
	v_cndmask_b32_e64 v129, 0, v245, s[100:101]
	v_cmp_le_i32_e64 s[96:97], 2, v76
	v_cmp_le_i32_e64 s[100:101], 3, v76
	s_nop 0
	v_cndmask_b32_e64 v130, 0, v246, s[96:97]
	v_cndmask_b32_e64 v131, 0, v247, s[100:101]
	s_bfe_u32 s96, s62, 0x20006
	s_and_b32 s97, s96, 1
	s_mul_i32 s97, s97, 0x2700
	s_mov_b32 s101, 0x1c000
	s_mov_b32 s100, 0x6100
	s_bitcmp0_b32 s65, 0
	s_cselect_b32 s101, 0xe000, s101
	s_cselect_b32 s100, 0x4e00, s100
	s_cmp_gt_u32 s96, 1
	s_cselect_b32 s100, s100, 0
	s_add_i32 s97, s97, s101
	s_add_i32 s97, s97, s100
	v_xor_b32_e32 v74, v224, v234
	v_lshl_add_u32 v74, v74, 4, s97
	ds_write_b128 v74, v[128:131] offset:8448
	v_lshlrev_b32_e32 v75, 7, v234
	v_lshl_add_u32 v75, v233, 2, v75
	v_add_u32_e32 v75, s97, v75
	v_cmp_le_i32_e64 s[96:97], 0, v77
	v_cmp_le_i32_e64 s[100:101], 1, v77
	s_nop 0
	v_cndmask_b32_e64 v132, 0, v244, s[96:97]
	v_cndmask_b32_e64 v133, 0, v245, s[100:101]
	v_cmp_le_i32_e64 s[96:97], 2, v77
	v_cmp_le_i32_e64 s[100:101], 3, v77
	s_nop 0
	v_cndmask_b32_e64 v134, 0, v246, s[96:97]
	v_cndmask_b32_e64 v135, 0, v247, s[100:101]
	s_mov_b64 exec, 0x00ff00ff
	ds_write_b32 v75, v132 offset:9472
	ds_write_b32 v75, v133 offset:9504
	ds_write_b32 v75, v134 offset:9536
	ds_write_b32 v75, v135 offset:9568
	s_mov_b64 exec, -1
	s_branch .LBB0_655
	s_nop 0
	s_nop 0
	s_nop 0
	s_nop 0
	s_nop 0
	s_nop 0
	s_nop 0
	s_nop 0
	s_nop 0
	s_nop 0
	s_nop 0
	s_nop 0
	s_nop 0
	s_nop 0
	s_nop 0
	s_nop 0
	s_nop 0
	s_nop 0
	s_nop 0
	s_nop 0
	s_nop 0
	s_nop 0
	s_nop 0
	s_nop 0
	s_nop 0
	s_nop 0
	s_nop 0
	s_nop 0
	s_nop 0
	s_nop 0
	s_nop 0
	s_nop 0
	s_nop 0
	s_nop 0
	s_nop 0
	s_nop 0
	s_nop 0
	s_nop 0
	s_nop 0
	s_nop 0
	s_nop 0
	s_nop 0
	s_nop 0
	s_nop 0
	s_nop 0
	s_nop 0
	s_nop 0
	s_nop 0
	s_nop 0
